# staging loops with all loads in flight: P3 relative-position table (15 serial L2 round trips -> 1) and P0 GEMV silu(c) staging (5 -> 1 per unit); on top of v113
# speedup vs baseline: 1.0155x; 1.0056x over previous
.LBB0_27:
	s_mul_hi_i32 s0, s71, 0x2aaaaaab
	s_lshr_b32 s1, s0, 31
	s_ashr_i32 s72, s0, 4
	s_add_i32 s72, s72, s1
	s_lshl_b32 s2, s72, 9
	v_or_b32_e32 v2, s2, v0
	v_ashrrev_i32_e32 v3, 31, v2
	v_lshl_add_u64 v[4:5], v[2:3], 2, s[22:23]
	s_mov_b64 s[0:1], 0
	v_mov_b32_e32 v6, v1
	v_mov_b32_e32 v7, v0
	v_lshlrev_b32_e32 v205, 2, v2
	v_add_u32_e32 v206, 0x4000, v205
	v_add_u32_e32 v207, 0x8000, v205
	v_add_u32_e32 v208, 0xc000, v205
	global_load_dword v200, v205, s[18:19]
	global_load_dword v201, v206, s[18:19]
	global_load_dword v202, v207, s[18:19]
	global_load_dword v203, v208, s[18:19]
	global_load_dword v204, v205, s[22:23]
	s_waitcnt vmcnt(0)
	v_mul_f32_e32 v8, 0xbfb8aa3b, v200
	v_exp_f32_e32 v8, v8
	s_nop 0
	v_add_f32_e32 v8, 1.0, v8
	v_div_scale_f32 v9, s[4:5], v8, v8, v200
	v_rcp_f32_e32 v10, v9
	v_div_scale_f32 v11, vcc, v200, v8, v200
	v_fma_f32 v12, -v9, v10, 1.0
	v_fmac_f32_e32 v10, v12, v10
	v_mul_f32_e32 v12, v11, v10
	v_fma_f32 v13, -v9, v12, v11
	v_fmac_f32_e32 v12, v13, v10
	v_fma_f32 v9, -v9, v12, v11
	v_div_fmas_f32 v9, v9, v10, v12
	v_div_fixup_f32 v200, v9, v8, v200
	ds_write_b32 v6, v200
	v_mul_f32_e32 v8, 0xbfb8aa3b, v201
	v_exp_f32_e32 v8, v8
	s_nop 0
	v_add_f32_e32 v8, 1.0, v8
	v_div_scale_f32 v9, s[4:5], v8, v8, v201
	v_rcp_f32_e32 v10, v9
	v_div_scale_f32 v11, vcc, v201, v8, v201
	v_fma_f32 v12, -v9, v10, 1.0
	v_fmac_f32_e32 v10, v12, v10
	v_mul_f32_e32 v12, v11, v10
	v_fma_f32 v13, -v9, v12, v11
	v_fmac_f32_e32 v12, v13, v10
	v_fma_f32 v9, -v9, v12, v11
	v_div_fmas_f32 v9, v9, v10, v12
	v_div_fixup_f32 v201, v9, v8, v201
	ds_write_b32 v6, v201 offset:2048
	v_mul_f32_e32 v8, 0xbfb8aa3b, v202
	v_exp_f32_e32 v8, v8
	s_nop 0
	v_add_f32_e32 v8, 1.0, v8
	v_div_scale_f32 v9, s[4:5], v8, v8, v202
	v_rcp_f32_e32 v10, v9
	v_div_scale_f32 v11, vcc, v202, v8, v202
	v_fma_f32 v12, -v9, v10, 1.0
	v_fmac_f32_e32 v10, v12, v10
	v_mul_f32_e32 v12, v11, v10
	v_fma_f32 v13, -v9, v12, v11
	v_fmac_f32_e32 v12, v13, v10
	v_fma_f32 v9, -v9, v12, v11
	v_div_fmas_f32 v9, v9, v10, v12
	v_div_fixup_f32 v202, v9, v8, v202
	ds_write_b32 v6, v202 offset:4096
	v_mul_f32_e32 v8, 0xbfb8aa3b, v203
	v_exp_f32_e32 v8, v8
	s_nop 0
	v_add_f32_e32 v8, 1.0, v8
	v_div_scale_f32 v9, s[4:5], v8, v8, v203
	v_rcp_f32_e32 v10, v9
	v_div_scale_f32 v11, vcc, v203, v8, v203
	v_fma_f32 v12, -v9, v10, 1.0
	v_fmac_f32_e32 v10, v12, v10
	v_mul_f32_e32 v12, v11, v10
	v_fma_f32 v13, -v9, v12, v11
	v_fmac_f32_e32 v12, v13, v10
	v_fma_f32 v9, -v9, v12, v11
	v_div_fmas_f32 v9, v9, v10, v12
	v_div_fixup_f32 v203, v9, v8, v203
	ds_write_b32 v6, v203 offset:6144
	v_mul_f32_e32 v8, 0xbfb8aa3b, v204
	v_exp_f32_e32 v8, v8
	s_nop 0
	v_add_f32_e32 v8, 1.0, v8
	v_div_scale_f32 v9, s[4:5], v8, v8, v204
	v_rcp_f32_e32 v10, v9
	v_div_scale_f32 v11, vcc, v204, v8, v204
	v_fma_f32 v12, -v9, v10, 1.0
	v_fmac_f32_e32 v10, v12, v10
	v_mul_f32_e32 v12, v11, v10
	v_fma_f32 v13, -v9, v12, v11
	v_fmac_f32_e32 v12, v13, v10
	v_fma_f32 v9, -v9, v12, v11
	v_div_fmas_f32 v9, v9, v10, v12
	v_div_fixup_f32 v204, v9, v8, v204
	ds_write_b32 v6, v204 offset:8192
	v_mov_b32_e32 v3, v204
	v_add_u32_e32 v2, 0x5000, v2
	v_add_u32_e32 v6, 0x2800, v6
	v_add_u32_e32 v7, 0xa00, v7
	s_or_b64 exec, exec, s[0:1]
	v_readfirstlane_b32 s4, v55
	s_mul_i32 s0, s72, 0x60
	s_add_i32 s1, s4, s2
	s_sub_i32 s0, s71, s0
	s_mul_hi_i32 s2, s1, 0x18000
	s_mul_i32 s1, s1, 0x18000
	s_add_u32 s5, s24, s1
	s_addc_u32 s73, s25, s2
	s_lshl_b32 s0, s0, 8
	s_ashr_i32 s1, s0, 31
	s_lshl_b64 s[2:3], s[0:1], 2
	s_add_u32 s2, s5, s2
	s_addc_u32 s3, s73, s3
	s_lshl_b32 s1, s4, 2
	v_mov_b32_e32 v22, 0
	v_lshl_add_u64 v[30:31], s[2:3], 0, v[28:29]
	s_add_i32 s1, s1, 0
	s_mov_b64 s[2:3], 0
	v_mov_b32_e32 v23, v22
	v_mov_b32_e32 v24, v22
	v_mov_b32_e32 v25, v22
	v_mov_b32_e32 v42, v22
	v_mov_b32_e32 v43, v22
	v_mov_b32_e32 v36, v22
	v_mov_b32_e32 v37, v22
	v_mov_b32_e32 v46, v22
	v_mov_b32_e32 v47, v22
	v_mov_b32_e32 v38, v22
	v_mov_b32_e32 v39, v22
	v_mov_b32_e32 v48, v22
	v_mov_b32_e32 v49, v22
	v_mov_b32_e32 v40, v22
	v_mov_b32_e32 v41, v22
	v_mov_b32_e32 v50, v22
	v_mov_b32_e32 v51, v22
	v_mov_b32_e32 v44, v22
	v_mov_b32_e32 v45, v22
	s_waitcnt lgkmcnt(0)
	s_barrier
	s_branch .LBB0_31

.LBB0_525:
	s_add_u32 s4, s54, 0x42600000
	s_addc_u32 s5, s55, 0
	s_add_u32 s6, s54, 0x2b600000
	s_addc_u32 s7, s55, 0
	s_cmp_lt_i32 s58, 4
	s_cselect_b64 s[0:1], -1, 0
	s_cmp_gt_i32 s59, 3
	s_cselect_b64 s[2:3], -1, 0
	s_and_b64 s[0:1], s[0:1], s[2:3]
	s_andn2_b64 vcc, exec, s[0:1]
	s_cbranch_vccnz .LBB0_604
	s_waitcnt vmcnt(0)
	v_lshlrev_b32_e32 v2, 2, v0
	v_add_u32_e32 v1, 0x400, v2
	v_add_u32_e32 v3, 0x1000, v2
	v_add_u32_e32 v4, 0x2000, v2
	v_add_u32_e32 v5, 0x3000, v2
	v_add_u32_e32 v6, 0x4000, v2
	v_add_u32_e32 v7, 0x5000, v2
	v_add_u32_e32 v8, 0x6000, v2
	v_add_u32_e32 v9, 0x7000, v2
	global_load_dword v200, v2, s[38:39]
	global_load_dword v201, v2, s[38:39] offset:2048
	global_load_dword v202, v3, s[38:39]
	global_load_dword v203, v3, s[38:39] offset:2048
	global_load_dword v204, v4, s[38:39]
	global_load_dword v205, v4, s[38:39] offset:2048
	global_load_dword v206, v5, s[38:39]
	global_load_dword v207, v5, s[38:39] offset:2048
	global_load_dword v208, v6, s[38:39]
	global_load_dword v209, v6, s[38:39] offset:2048
	global_load_dword v210, v7, s[38:39]
	global_load_dword v211, v7, s[38:39] offset:2048
	global_load_dword v212, v8, s[38:39]
	global_load_dword v213, v8, s[38:39] offset:2048
	v_cmp_gt_u32_e32 vcc, 0x110, v0
	s_mov_b64 s[2:3], vcc
	s_and_saveexec_b64 s[0:1], vcc
	global_load_dword v214, v9, s[38:39]
	s_or_b64 exec, exec, s[0:1]
	s_waitcnt vmcnt(0)
	v_mul_f32_e32 v200, 0x3fb8aa3b, v200
	v_mul_f32_e32 v201, 0x3fb8aa3b, v201
	v_mul_f32_e32 v202, 0x3fb8aa3b, v202
	v_mul_f32_e32 v203, 0x3fb8aa3b, v203
	v_mul_f32_e32 v204, 0x3fb8aa3b, v204
	v_mul_f32_e32 v205, 0x3fb8aa3b, v205
	v_mul_f32_e32 v206, 0x3fb8aa3b, v206
	v_mul_f32_e32 v207, 0x3fb8aa3b, v207
	v_mul_f32_e32 v208, 0x3fb8aa3b, v208
	v_mul_f32_e32 v209, 0x3fb8aa3b, v209
	v_mul_f32_e32 v210, 0x3fb8aa3b, v210
	v_mul_f32_e32 v211, 0x3fb8aa3b, v211
	v_mul_f32_e32 v212, 0x3fb8aa3b, v212
	v_mul_f32_e32 v213, 0x3fb8aa3b, v213
	ds_write_b32 v1, v200
	ds_write_b32 v1, v201 offset:2048
	ds_write_b32 v1, v202 offset:4096
	ds_write_b32 v1, v203 offset:6144
	ds_write_b32 v1, v204 offset:8192
	ds_write_b32 v1, v205 offset:10240
	ds_write_b32 v1, v206 offset:12288
	ds_write_b32 v1, v207 offset:14336
	ds_write_b32 v1, v208 offset:16384
	ds_write_b32 v1, v209 offset:18432
	ds_write_b32 v1, v210 offset:20480
	ds_write_b32 v1, v211 offset:22528
	ds_write_b32 v1, v212 offset:24576
	ds_write_b32 v1, v213 offset:26624
	s_and_saveexec_b64 s[0:1], s[2:3]
	v_mul_f32_e32 v214, 0x3fb8aa3b, v214
	ds_write_b32 v1, v214 offset:28672
	s_or_b64 exec, exec, s[0:1]
	s_cmpk_gt_i32 s14, 0x1ff
	s_waitcnt lgkmcnt(0)
	s_barrier
	s_cbranch_scc1 .LBB0_550
	v_and_b32_e32 v1, 31, v0
	s_lshl_b32 s0, s92, 5
	v_lshrrev_b32_e32 v5, 4, v178
	v_and_or_b32 v146, s0, 32, v1
	v_lshlrev_b32_e32 v1, 2, v5
	s_bfe_u32 s0, s95, 0x20006
	v_and_b32_e32 v7, 15, v0
	v_lshrrev_b32_e32 v8, 1, v178
	v_bitop3_b32 v7, s0, v7, v1 bitop3:0x36
	v_lshlrev_b32_e32 v1, 1, v0
	v_and_b32_e32 v8, 4, v8
	v_and_or_b32 v1, v1, 8, v8
	v_lshrrev_b32_e32 v4, 5, v178
	v_and_or_b32 v8, v0, 19, v1
	v_and_b32_e32 v2, 12, v2
	v_lshrrev_b32_e32 v9, 2, v1
	v_lshlrev_b32_e32 v1, 8, v8
	v_bitop3_b32 v8, v9, v4, v2 bitop3:0x36
	v_lshlrev_b32_e32 v147, 4, v8
	v_or_b32_e32 v8, 2, v4
	v_bitop3_b32 v8, v9, v8, v2 bitop3:0x36
	v_lshlrev_b32_e32 v156, 4, v8
	v_or_b32_e32 v8, 4, v4
	v_bitop3_b32 v8, v9, v8, v2 bitop3:0x36
	v_lshlrev_b32_e32 v157, 4, v8
	v_or_b32_e32 v8, 6, v4
	v_bitop3_b32 v8, v9, v8, v2 bitop3:0x36
	v_lshlrev_b32_e32 v158, 4, v8
	v_or_b32_e32 v8, 8, v4
	v_bitop3_b32 v8, v9, v8, v2 bitop3:0x36
	v_lshlrev_b32_e32 v159, 4, v8
	v_or_b32_e32 v8, 10, v4
	v_bitop3_b32 v8, v9, v8, v2 bitop3:0x36
	v_lshlrev_b32_e32 v160, 4, v8
	v_or_b32_e32 v8, 12, v4
	v_bitop3_b32 v8, v9, v8, v2 bitop3:0x36
	v_lshlrev_b32_e32 v161, 4, v8
	v_or_b32_e32 v8, 14, v4
	v_bitop3_b32 v2, v9, v8, v2 bitop3:0x36
	v_lshlrev_b32_e32 v162, 4, v2
	v_lshlrev_b32_e32 v2, 12, v5
	v_lshl_or_b32 v2, s92, 14, v2
	v_lshl_or_b32 v148, v7, 4, v2
	v_lshrrev_b32_e32 v7, 3, v178
	v_bfe_u32 v8, v178, 1, 1
	v_and_or_b32 v7, v7, 2, v8
	v_lshlrev_b32_e32 v8, 3, v0
	v_mov_b32_e32 v9, 0x2000
	v_lshlrev_b32_e32 v6, 3, v4
	v_bfe_u32 v2, v0, 2, 2
	v_and_b32_e32 v5, 12, v0
	v_and_or_b32 v8, v8, 8, v9
	v_lshlrev_b32_e32 v9, 1, v4
	v_or_b32_e32 v2, v2, v6
	v_or_b32_e32 v10, v9, v5
	v_lshl_or_b32 v11, v2, 8, v8
	v_bitop3_b32 v12, v7, v10, 4 bitop3:0x36
	v_bitop3_b32 v13, v7, v10, 8 bitop3:0x36
	v_bitop3_b32 v10, v7, v10, 12 bitop3:0x36
	v_or_b32_e32 v2, 4, v2
	v_bitop3_b32 v9, v9, v7, v5 bitop3:0x36
	v_lshl_or_b32 v166, v10, 4, v11
	v_lshrrev_b32_e32 v10, 2, v2
	v_lshl_or_b32 v163, v9, 4, v11
	v_or_b32_e32 v9, 4, v7
	v_lshl_or_b32 v164, v12, 4, v11
	v_or_b32_e32 v12, 8, v7
	v_lshl_or_b32 v165, v13, 4, v11
	v_or_b32_e32 v13, 12, v7
	v_lshl_or_b32 v2, v2, 8, v8
	v_bitop3_b32 v7, v10, v7, v5 bitop3:0x36
	v_lshl_or_b32 v167, v7, 4, v2
	v_bitop3_b32 v7, v10, v9, v5 bitop3:0x36
	v_sub_u32_e64 v3, v146, 8 clamp
	v_lshl_or_b32 v168, v7, 4, v2
	v_bitop3_b32 v7, v10, v12, v5 bitop3:0x36
	v_bitop3_b32 v5, v10, v13, v5 bitop3:0x36
	v_lshl_or_b32 v169, v7, 4, v2
	v_lshl_or_b32 v170, v5, 4, v2
	v_min_u32_e32 v2, 48, v3
	s_lshl_b32 s0, s92, 10
	v_sub_u32_e32 v171, v6, v2
	v_sub_u32_e32 v2, v6, v146
	v_mov_b32_e32 v151, 0
	s_add_i32 s13, s0, 0
	v_lshl_add_u32 v172, v2, 2, 0
	v_mbcnt_lo_u32_b32 v2, -1, 0
	s_lshr_b32 s12, s95, 7
	v_mov_b32_e32 v149, v151
	s_mov_b32 s1, 0
	v_cmp_gt_u32_e64 s[2:3], 32, v178
	v_lshlrev_b32_e32 v152, 1, v6
	v_mov_b32_e32 v153, v151
	s_add_i32 s15, s13, 0x8000
	s_add_i32 s24, s13, 0xa000
	s_add_i32 s25, s13, 0xc000
	s_add_i32 s35, s13, 0xe000
	s_add_i32 s46, s13, 0x10000
	s_add_i32 s47, s13, 0x12000
	s_add_i32 s57, s13, 0x14000
	s_add_i32 s60, s13, 0x16000
	s_add_i32 s61, s13, 0x18000
	s_add_i32 s63, s13, 0x1a000
	s_movk_i32 s70, 0xffef
	v_lshlrev_b32_e32 v150, 3, v4
	v_mov_b32_e32 v173, 0xff800000
	v_mbcnt_hi_u32_b32 v174, -1, v2
	v_xor_b32_e32 v197, 32, v174
	v_lshlrev_b32_e32 v197, 2, v197
	v_add_u32_e32 v198, 0, v171
	v_cmp_gt_u32_e32 vcc, 16, v198
	s_nop 1
	v_cndmask_b32_e32 v222, v173, v151, vcc
	v_add_u32_e32 v198, 1, v171
	v_cmp_gt_u32_e32 vcc, 16, v198
	s_nop 1
	v_cndmask_b32_e32 v223, v173, v151, vcc
	v_add_u32_e32 v198, 2, v171
	v_cmp_gt_u32_e32 vcc, 16, v198
	s_nop 1
	v_cndmask_b32_e32 v224, v173, v151, vcc
	v_add_u32_e32 v198, 3, v171
	v_cmp_gt_u32_e32 vcc, 16, v198
	s_nop 1
	v_cndmask_b32_e32 v225, v173, v151, vcc
	v_add_u32_e32 v198, 4, v171
	v_cmp_gt_u32_e32 vcc, 16, v198
	s_nop 1
	v_cndmask_b32_e32 v226, v173, v151, vcc
	v_add_u32_e32 v198, 5, v171
	v_cmp_gt_u32_e32 vcc, 16, v198
	s_nop 1
	v_cndmask_b32_e32 v227, v173, v151, vcc
	v_add_u32_e32 v198, 6, v171
	v_cmp_gt_u32_e32 vcc, 16, v198
	s_nop 1
	v_cndmask_b32_e32 v228, v173, v151, vcc
	v_add_u32_e32 v198, 7, v171
	v_cmp_gt_u32_e32 vcc, 16, v198
	s_nop 1
	v_cndmask_b32_e32 v229, v173, v151, vcc
	v_add_u32_e32 v198, 16, v171
	v_cmp_gt_u32_e32 vcc, 16, v198
	s_nop 1
	v_cndmask_b32_e32 v230, v173, v151, vcc
	v_add_u32_e32 v198, 17, v171
	v_cmp_gt_u32_e32 vcc, 16, v198
	s_nop 1
	v_cndmask_b32_e32 v231, v173, v151, vcc
	v_add_u32_e32 v198, 18, v171
	v_cmp_gt_u32_e32 vcc, 16, v198
	s_nop 1
	v_cndmask_b32_e32 v232, v173, v151, vcc
	v_add_u32_e32 v198, 19, v171
	v_cmp_gt_u32_e32 vcc, 16, v198
	s_nop 1
	v_cndmask_b32_e32 v233, v173, v151, vcc
	v_add_u32_e32 v198, 20, v171
	v_cmp_gt_u32_e32 vcc, 16, v198
	s_nop 1
	v_cndmask_b32_e32 v234, v173, v151, vcc
	v_add_u32_e32 v198, 21, v171
	v_cmp_gt_u32_e32 vcc, 16, v198
	s_nop 1
	v_cndmask_b32_e32 v235, v173, v151, vcc
	v_add_u32_e32 v198, 22, v171
	v_cmp_gt_u32_e32 vcc, 16, v198
	s_nop 1
	v_cndmask_b32_e32 v236, v173, v151, vcc
	v_add_u32_e32 v198, 23, v171
	v_cmp_gt_u32_e32 vcc, 16, v198
	s_nop 1
	v_cndmask_b32_e32 v237, v173, v151, vcc
	v_add_u32_e32 v198, 32, v171
	v_cmp_gt_u32_e32 vcc, 16, v198
	s_nop 1
	v_cndmask_b32_e32 v238, v173, v151, vcc
	v_add_u32_e32 v198, 33, v171
	v_cmp_gt_u32_e32 vcc, 16, v198
	s_nop 1
	v_cndmask_b32_e32 v239, v173, v151, vcc
	v_add_u32_e32 v198, 34, v171
	v_cmp_gt_u32_e32 vcc, 16, v198
	s_nop 1
	v_cndmask_b32_e32 v240, v173, v151, vcc
	v_add_u32_e32 v198, 35, v171
	v_cmp_gt_u32_e32 vcc, 16, v198
	s_nop 1
	v_cndmask_b32_e32 v241, v173, v151, vcc
	v_add_u32_e32 v198, 36, v171
	v_cmp_gt_u32_e32 vcc, 16, v198
	s_nop 1
	v_cndmask_b32_e32 v242, v173, v151, vcc
	v_add_u32_e32 v198, 37, v171
	v_cmp_gt_u32_e32 vcc, 16, v198
	s_nop 1
	v_cndmask_b32_e32 v243, v173, v151, vcc
	v_add_u32_e32 v198, 38, v171
	v_cmp_gt_u32_e32 vcc, 16, v198
	s_nop 1
	v_cndmask_b32_e32 v244, v173, v151, vcc
	v_add_u32_e32 v198, 39, v171
	v_cmp_gt_u32_e32 vcc, 16, v198
	s_nop 1
	v_cndmask_b32_e32 v245, v173, v151, vcc
	v_add_u32_e32 v198, 48, v171
	v_cmp_gt_u32_e32 vcc, 16, v198
	s_nop 1
	v_cndmask_b32_e32 v246, v173, v151, vcc
	v_add_u32_e32 v198, 49, v171
	v_cmp_gt_u32_e32 vcc, 16, v198
	s_nop 1
	v_cndmask_b32_e32 v247, v173, v151, vcc
	v_add_u32_e32 v198, 50, v171
	v_cmp_gt_u32_e32 vcc, 16, v198
	s_nop 1
	v_cndmask_b32_e32 v248, v173, v151, vcc
	v_add_u32_e32 v198, 51, v171
	v_cmp_gt_u32_e32 vcc, 16, v198
	s_nop 1
	v_cndmask_b32_e32 v249, v173, v151, vcc
	v_add_u32_e32 v198, 52, v171
	v_cmp_gt_u32_e32 vcc, 16, v198
	s_nop 1
	v_cndmask_b32_e32 v250, v173, v151, vcc
	v_add_u32_e32 v198, 53, v171
	v_cmp_gt_u32_e32 vcc, 16, v198
	s_nop 1
	v_cndmask_b32_e32 v251, v173, v151, vcc
	v_add_u32_e32 v198, 54, v171
	v_cmp_gt_u32_e32 vcc, 16, v198
	s_nop 1
	v_cndmask_b32_e32 v252, v173, v151, vcc
	v_add_u32_e32 v198, 55, v171
	v_cmp_gt_u32_e32 vcc, 16, v198
	s_nop 1
	v_cndmask_b32_e32 v253, v173, v151, vcc
	s_branch .LBB0_531
